# bg barrier: early invalidate issued by wave 1 and status word read with ds_read (no vmcnt stall), so the first background unit is not delayed by the invalidate
# baseline (speedup 1.0000x reference)
; DI unsigned xb_ld(unsigned* p) { return __hip_atomic_load(p, __ATOMIC_RELAXED, __HIP_MEMORY_SCOPE_AGENT); }
; template <class BG>
; DI void xcd_barrier_bg(const XcdBarrier b, char* smem, BG bg) {
;     ...
;   __syncthreads();
;   if (*sst == 0u) {
;     bool more = true;
;     unsigned polls = 0u;
;     for (;;) {
;       if (threadIdx.x == 0) {
;         bool rel = xb_ld(&b.bar[XB_XGEN(b.x)]) != mygen;
;         if (!rel && (++polls & 1023u) == 0u) { if (xb_ld(&b.bar[XB_TMO])) rel = true; else if (polls > XB_SPIN_CAP) { atomicAdd(&b.bar[XB_TMO], 1u); rel = true; } }
;         *sst = rel ? 2u : 0u;
;       }
;       __syncthreads();
;       const unsigned stv = *sst;
;       if (stv == 2u) break;
;       if (more) more = bg(); else __builtin_amdgcn_s_sleep(2);
.LBB0_52:
	s_or_b64 exec, exec, s[86:87]
	s_add_i32 s13, 0, 12
	s_mov_b64 s[4:5], src_shared_base
	s_cmp_lg_u32 s13, -1
	s_cselect_b32 s4, s13, 0
	s_cselect_b32 s5, s5, 0
	s_waitcnt lgkmcnt(0)
	v_mov_b32_e32 v2, s4
	v_mov_b32_e32 v3, s5
	s_barrier
	flat_load_dword v2, v[2:3] sc0 sc1
	s_waitcnt vmcnt(0)
	s_mov_b32 s5, 0
	s_waitcnt lgkmcnt(0)
	v_cmp_eq_u32_e32 vcc, 0, v2
	s_and_saveexec_b64 s[14:15], vcc
	s_cbranch_execz .LBB0_102
	v_readfirstlane_b32 s96, v0
	s_sub_u32 s96, s96, 64
	s_cmp_lt_u32 s96, 64
	s_cbranch_scc0 .Lbinv_1
	buffer_inv sc1

; DI unsigned xb_ld(unsigned* p) { return __hip_atomic_load(p, __ATOMIC_RELAXED, __HIP_MEMORY_SCOPE_AGENT); }
; template <class BG>
; DI void xcd_barrier_bg(const XcdBarrier b, char* smem, BG bg) {
;     ...
;     for (;;) {
;       if (threadIdx.x == 0) {
;         bool rel = xb_ld(&b.bar[XB_XGEN(b.x)]) != mygen;
;         if (!rel && (++polls & 1023u) == 0u) { if (xb_ld(&b.bar[XB_TMO])) rel = true; else if (polls > XB_SPIN_CAP) { atomicAdd(&b.bar[XB_TMO], 1u); rel = true; } }
;         *sst = rel ? 2u : 0u;
;       }
;       __syncthreads();
;       const unsigned stv = *sst;
;       if (stv == 2u) break;
;       if (more) more = bg(); else __builtin_amdgcn_s_sleep(2);
;       __syncthreads();
.LBB0_70:
	s_or_b64 exec, exec, s[8:9]
	s_xor_b64 s[8:9], s[6:7], -1
	s_cmp_lg_u32 s13, -1
	s_cselect_b32 s6, s13, 0
	s_cselect_b32 s7, s17, 0
	v_mov_b32_e32 v2, s6
	v_mov_b32_e32 v3, s7
	s_waitcnt lgkmcnt(0)
	s_barrier
	ds_read_b32 v2, v2
	s_mov_b64 s[10:11], -1
	s_waitcnt lgkmcnt(0)
	v_cmp_ne_u32_e32 vcc, 2, v2
	s_and_saveexec_b64 s[24:25], vcc
	s_cbranch_execz .LBB0_57
	s_and_saveexec_b64 s[6:7], s[8:9]
	s_xor_b64 s[6:7], exec, s[6:7]
	s_sleep 2
	s_or_saveexec_b64 s[26:27], s[6:7]
	s_mov_b64 s[6:7], 0
	s_xor_b64 exec, exec, s[26:27]
	s_cbranch_execz .LBB0_56
	s_barrier
	s_and_saveexec_b64 s[6:7], s[2:3]
	s_cbranch_execz .LBB0_78
	s_mov_b64 s[10:11], exec
	v_mbcnt_lo_u32_b32 v2, s10, 0
	v_mbcnt_hi_u32_b32 v2, s11, v2
	v_cmp_eq_u32_e32 vcc, 0, v2
	s_and_saveexec_b64 s[8:9], vcc
	s_cbranch_execz .LBB0_77
	s_bcnt1_i32_b64 s10, s[10:11]
	v_mov_b32_e32 v3, s10
	global_atomic_add v3, v39, v3, s[18:19] sc0

; DI unsigned xb_ld(unsigned* p) { return __hip_atomic_load(p, __ATOMIC_RELAXED, __HIP_MEMORY_SCOPE_AGENT); }
; template <class BG>
; DI void xcd_barrier_bg(const XcdBarrier b, char* smem, BG bg) {
;     ...
;   __syncthreads();
;   if (*sst == 0u) {
;     bool more = true;
;     unsigned polls = 0u;
;     for (;;) {
;       if (threadIdx.x == 0) {
;         bool rel = xb_ld(&b.bar[XB_XGEN(b.x)]) != mygen;
;         if (!rel && (++polls & 1023u) == 0u) { if (xb_ld(&b.bar[XB_TMO])) rel = true; else if (polls > XB_SPIN_CAP) { atomicAdd(&b.bar[XB_TMO], 1u); rel = true; } }
;         *sst = rel ? 2u : 0u;
;       }
;       __syncthreads();
;       const unsigned stv = *sst;
;       if (stv == 2u) break;
;       if (more) more = bg(); else __builtin_amdgcn_s_sleep(2);
.LBB0_224:
	s_or_b64 exec, exec, s[42:43]
	s_add_i32 s13, 0, 12
	s_mov_b64 s[4:5], src_shared_base
	s_cmp_lg_u32 s13, -1
	s_cselect_b32 s4, s13, 0
	s_cselect_b32 s5, s5, 0
	s_waitcnt lgkmcnt(0)
	v_mov_b32_e32 v2, s4
	v_mov_b32_e32 v3, s5
	s_barrier
	flat_load_dword v2, v[2:3] sc0 sc1
	s_waitcnt vmcnt(0)
	s_mov_b32 s5, 0
	s_waitcnt lgkmcnt(0)
	v_cmp_eq_u32_e32 vcc, 0, v2
	s_and_saveexec_b64 s[14:15], vcc
	s_cbranch_execz .LBB0_274
	v_readfirstlane_b32 s96, v0
	s_sub_u32 s96, s96, 64
	s_cmp_lt_u32 s96, 64
	s_cbranch_scc0 .Lbinv_2
	buffer_inv sc1

; DI unsigned xb_ld(unsigned* p) { return __hip_atomic_load(p, __ATOMIC_RELAXED, __HIP_MEMORY_SCOPE_AGENT); }
; template <class BG>
; DI void xcd_barrier_bg(const XcdBarrier b, char* smem, BG bg) {
;     ...
;   __syncthreads();
;   if (*sst == 0u) {
;     bool more = true;
;     unsigned polls = 0u;
;     for (;;) {
;       if (threadIdx.x == 0) {
;         bool rel = xb_ld(&b.bar[XB_XGEN(b.x)]) != mygen;
;         if (!rel && (++polls & 1023u) == 0u) { if (xb_ld(&b.bar[XB_TMO])) rel = true; else if (polls > XB_SPIN_CAP) { atomicAdd(&b.bar[XB_TMO], 1u); rel = true; } }
;         *sst = rel ? 2u : 0u;
;       }
;       __syncthreads();
;       const unsigned stv = *sst;
;       if (stv == 2u) break;
;       if (more) more = bg(); else __builtin_amdgcn_s_sleep(2);
.LBB0_331:
	s_or_b64 exec, exec, s[40:41]
	s_add_i32 s13, 0, 12
	s_mov_b64 s[4:5], src_shared_base
	s_cmp_lg_u32 s13, -1
	s_cselect_b32 s4, s13, 0
	s_cselect_b32 s5, s5, 0
	s_waitcnt lgkmcnt(0)
	v_mov_b32_e32 v2, s4
	v_mov_b32_e32 v3, s5
	s_barrier
	flat_load_dword v2, v[2:3] sc0 sc1
	s_waitcnt vmcnt(0)
	s_mov_b32 s5, 0
	s_waitcnt lgkmcnt(0)
	v_cmp_eq_u32_e32 vcc, 0, v2
	s_and_saveexec_b64 s[14:15], vcc
	s_cbranch_execz .LBB0_381
	v_readfirstlane_b32 s96, v0
	s_sub_u32 s96, s96, 64
	s_cmp_lt_u32 s96, 64
	s_cbranch_scc0 .Lbinv_3
	buffer_inv sc1
